# DIFF attention tile body hand-scheduled: K/V fragment ds_reads hoisted into distinct registers, QK MFMAs back to back, exp/cvt interleaved 2+1 per PV MFMA gap (same MFMA order per accumulator); on top
# speedup vs baseline: 1.0088x; 1.0039x over previous
; #define LAS __attribute__((address_space(3)))
; __device__ __forceinline__ int crow(int r, int hi) { return (r & 3) + 8 * (r >> 2) + 4 * hi; }
; template <bool DIFF>
; __device__ __forceinline__ void attn_unit(CA& A, int l, int b, int hh, int qb, LAS unsigned char* lds, float lam, float lam_init) {
;     ...
;             const LAS unsigned char* Kb = lds + AL_KS + buf * AL_KSZ;
;             const LAS unsigned char* Vb = lds + AL_VT + buf * AL_VSZ;
;             f32x16 p[2];
; #pragma unroll
;             for (int kt = 0; kt < 2; ++kt) {
;                 if (!DIFF) {
;                     const LAS float* nc = (const LAS float*)(lds + AL_NC + buf * 512) + 32 * kt + 4 * hi;
; #pragma unroll
;                     for (int g = 0; g < 4; ++g) { const f32x4 c4 = *(const LAS f32x4*)(nc + 8 * g); p[kt][4 * g] = c4[0]; p[kt][4 * g + 1] = c4[1]; p[kt][4 * g + 2] = c4[2]; p[kt][4 * g + 3] = c4[3]; }
;                 }
; #pragma unroll
;                 for (int s = 0; s < NS; ++s) {
;                     const bf16x8 a = *(const LAS bf16x8*)(Kb + (32 * kt + r32) * 144 + (koff + 16 * s + 8 * hi) * 2);
;                     if (DIFF && s == 0) p[kt] = __builtin_amdgcn_mfma_f32_32x32x16_bf16(a, qf[s], negm, 0, 0, 0);
;                     else p[kt] = __builtin_amdgcn_mfma_f32_32x32x16_bf16(a, qf[s], p[kt], 0, 0, 0);
;                 }
;             }
;             if (!DIFF) {
; #pragma unroll
;                 for (int kt = 0; kt < 2; ++kt)
; #pragma unroll
;                     for (int r = 0; r < 16; ++r) p[kt][r] -= m_ref;
;             }
;             if (key0 + 63 > qfirst) {
; #pragma unroll
;                 for (int kt = 0; kt < 2; ++kt)
; #pragma unroll
;                     for (int r = 0; r < 16; ++r) if (key0 + 32 * kt + crow(r, hi) > qmine) p[kt][r] = -1e30f;
;             }
.LBB0_748:
	s_mul_i32 s30, s29, 0x2400
	s_mul_i32 s37, s29, 0x2200
	v_add3_u32 v1, s30, v142, v143
	v_add3_u32 v146, s30, v144, v143
	ds_read_b128 v[148:151], v1
	ds_read_b128 v[152:155], v146
	ds_read_b128 v[156:159], v1 offset:32
	ds_read_b128 v[160:163], v146 offset:32
	v_add3_u32 v10, v141, s37, v145
	v_mov_b32_e32 v204, s36
	v_mov_b32_e32 v205, s36
	v_mov_b32_e32 v206, s36
	v_mov_b32_e32 v207, s36
	v_add_u32_e32 v14, 0x4800, v10
	v_add_u32_e32 v1, 0x5800, v10
	s_waitcnt lgkmcnt(2)
	v_mfma_f32_32x32x16_bf16 v[96:111], v[148:151], v[112:115], v[48:63]
	v_mfma_f32_32x32x16_bf16 v[80:95], v[152:155], v[112:115], v[48:63]
	s_waitcnt lgkmcnt(0)
	v_mfma_f32_32x32x16_bf16 v[96:111], v[156:159], v[116:119], v[96:111]
	v_mfma_f32_32x32x16_bf16 v[80:95], v[160:163], v[116:119], v[80:95]
	ds_read2_b64 v[164:167], v14 offset0:0 offset1:2
	ds_read2_b64 v[168:171], v1 offset0:32 offset1:34
	ds_read2_b64 v[172:175], v14 offset0:4 offset1:6
	ds_read2_b64 v[180:183], v1 offset0:36 offset1:38
	ds_read2_b64 v[184:187], v14 offset0:8 offset1:10
	ds_read2_b64 v[188:191], v1 offset0:40 offset1:42
	ds_read2_b64 v[192:195], v14 offset0:12 offset1:14
	ds_read2_b64 v[196:199], v1 offset0:44 offset1:46
	s_cmp_le_u32 s26, s25
	s_nop 1
	s_cbranch_scc1 .LBB0_750
	v_add_u32_e32 v1, s26, v131
	v_subrev_u32_e32 v2, 63, v1
	v_cmp_gt_u32_e32 vcc, v2, v138
	s_nop 1
	v_cndmask_b32_e32 v3, v96, v225, vcc
	v_cmp_lt_u32_e32 vcc, v2, v138
	v_subrev_u32_e32 v2, 61, v1
	s_nop 0
	v_cndmask_b32_e32 v96, v3, v96, vcc
	v_cndmask_b32_e32 v97, v225, v97, vcc
	v_cmp_le_u32_e32 vcc, v2, v138
	v_subrev_u32_e32 v2, 60, v1
	s_nop 0
	v_cndmask_b32_e32 v98, v225, v98, vcc
	v_cmp_le_u32_e32 vcc, v2, v138
	v_subrev_u32_e32 v2, 55, v1
	s_nop 0
	v_cndmask_b32_e32 v99, v225, v99, vcc
	v_cmp_le_u32_e32 vcc, v2, v138
	v_subrev_u32_e32 v2, 54, v1
	s_nop 0
	v_cndmask_b32_e32 v100, v225, v100, vcc
	v_cmp_le_u32_e32 vcc, v2, v138
	v_subrev_u32_e32 v2, 53, v1
	s_nop 0
	v_cndmask_b32_e32 v101, v225, v101, vcc
	v_cmp_le_u32_e32 vcc, v2, v138
	v_subrev_u32_e32 v2, 52, v1
	s_nop 0
	v_cndmask_b32_e32 v102, v225, v102, vcc
	v_cmp_le_u32_e32 vcc, v2, v138
	v_subrev_u32_e32 v2, 47, v1
	s_nop 0
	v_cndmask_b32_e32 v103, v225, v103, vcc
	v_cmp_le_u32_e32 vcc, v2, v138
	v_subrev_u32_e32 v2, 46, v1
	s_nop 0
	v_cndmask_b32_e32 v104, v225, v104, vcc
	v_cmp_le_u32_e32 vcc, v2, v138
	v_subrev_u32_e32 v2, 45, v1
	s_nop 0
	v_cndmask_b32_e32 v105, v225, v105, vcc
	v_cmp_le_u32_e32 vcc, v2, v138
	v_subrev_u32_e32 v2, 44, v1
	s_nop 0
	v_cndmask_b32_e32 v106, v225, v106, vcc
	v_cmp_le_u32_e32 vcc, v2, v138
	v_subrev_u32_e32 v2, 39, v1
	s_nop 0
	v_cndmask_b32_e32 v107, v225, v107, vcc
	v_cmp_le_u32_e32 vcc, v2, v138
	v_subrev_u32_e32 v2, 38, v1
	s_nop 0
	v_cndmask_b32_e32 v108, v225, v108, vcc
	v_cmp_le_u32_e32 vcc, v2, v138
	v_subrev_u32_e32 v2, 37, v1
	s_nop 0
	v_cndmask_b32_e32 v109, v225, v109, vcc
	v_cmp_le_u32_e32 vcc, v2, v138
	v_subrev_u32_e32 v2, 36, v1
	s_nop 0
	v_cndmask_b32_e32 v110, v225, v110, vcc
	v_cmp_le_u32_e32 vcc, v2, v138
	v_subrev_u32_e32 v2, 31, v1
	s_nop 0
	v_cndmask_b32_e32 v111, v225, v111, vcc
	v_cmp_le_u32_e32 vcc, v2, v138
	v_subrev_u32_e32 v2, 30, v1
	s_nop 0
	v_cndmask_b32_e32 v80, v225, v80, vcc
	v_cmp_le_u32_e32 vcc, v2, v138
	v_subrev_u32_e32 v2, 29, v1
	s_nop 0
	v_cndmask_b32_e32 v81, v225, v81, vcc
	v_cmp_le_u32_e32 vcc, v2, v138
	v_subrev_u32_e32 v2, 28, v1
	s_nop 0
	v_cndmask_b32_e32 v82, v225, v82, vcc
	v_cmp_le_u32_e32 vcc, v2, v138
	v_subrev_u32_e32 v2, 23, v1
	s_nop 0
	v_cndmask_b32_e32 v83, v225, v83, vcc
	v_cmp_le_u32_e32 vcc, v2, v138
	v_subrev_u32_e32 v2, 22, v1
	s_nop 0
	v_cndmask_b32_e32 v84, v225, v84, vcc
	v_cmp_le_u32_e32 vcc, v2, v138
	v_subrev_u32_e32 v2, 21, v1
	s_nop 0
	v_cndmask_b32_e32 v85, v225, v85, vcc
	v_cmp_le_u32_e32 vcc, v2, v138
	v_subrev_u32_e32 v2, 20, v1
	s_nop 0
	v_cndmask_b32_e32 v86, v225, v86, vcc
	v_cmp_le_u32_e32 vcc, v2, v138
	v_add_u32_e32 v2, -15, v1
	s_nop 0
	v_cndmask_b32_e32 v87, v225, v87, vcc
	v_cmp_le_u32_e32 vcc, v2, v138
	v_add_u32_e32 v2, -14, v1
	s_nop 0
	v_cndmask_b32_e32 v88, v225, v88, vcc
	v_cmp_le_u32_e32 vcc, v2, v138
	v_add_u32_e32 v2, -13, v1
	s_nop 0
	v_cndmask_b32_e32 v89, v225, v89, vcc
	v_cmp_le_u32_e32 vcc, v2, v138
	v_add_u32_e32 v2, -12, v1
	s_nop 0
	v_cndmask_b32_e32 v90, v225, v90, vcc
	v_cmp_le_u32_e32 vcc, v2, v138
	v_add_u32_e32 v2, -7, v1
	s_nop 0
	v_cndmask_b32_e32 v91, v225, v91, vcc
	v_cmp_le_u32_e32 vcc, v2, v138
	v_add_u32_e32 v2, -6, v1
	s_nop 0
	v_cndmask_b32_e32 v92, v225, v92, vcc
	v_cmp_le_u32_e32 vcc, v2, v138
	v_add_u32_e32 v2, -5, v1
	v_add_u32_e32 v1, -4, v1
	v_cndmask_b32_e32 v93, v225, v93, vcc
	v_cmp_le_u32_e32 vcc, v2, v138
	s_nop 1
	v_cndmask_b32_e32 v94, v225, v94, vcc
	v_cmp_le_u32_e32 vcc, v1, v138
	s_nop 1
	v_cndmask_b32_e32 v95, v225, v95, vcc
; #define LAS __attribute__((address_space(3)))
; __device__ __forceinline__ unsigned pk2(float lo, float hi) { f32x2_t v = {lo, hi}; bf16x2_t b = __builtin_convertvector(v, bf16x2_t); return __builtin_bit_cast(unsigned, b); }
; template <bool DIFF>
; __device__ __forceinline__ void attn_unit(CA& A, int l, int b, int hh, int qb, LAS unsigned char* lds, float lam, float lam_init) {
;     ...
;             first = false;
; #pragma unroll
;             for (int kt = 0; kt < 2; ++kt)
; #pragma unroll
;                 for (int r = 0; r < 16; ++r) p[kt][r] = __builtin_amdgcn_exp2f(p[kt][r]);
;             bf16x8 pb[2][2];
; #pragma unroll
;             for (int kt = 0; kt < 2; ++kt)
; #pragma unroll
;                 for (int i = 0; i < 2; ++i) { v4u w;
; #pragma unroll
;                     for (int j = 0; j < 4; ++j) w[j] = pk2(p[kt][8 * i + 2 * j], p[kt][8 * i + 2 * j + 1]);
;                     pb[kt][i] = __builtin_bit_cast(bf16x8, w); }
; #pragma unroll
;             for (int kt = 0; kt < 2; ++kt)
; #pragma unroll
;                 for (int i = 0; i < 2; ++i) {
; #pragma unroll
;                     for (int dt = 0; dt < 2; ++dt) {
;                         const LAS unsigned char* vq = Vb + (32 * dt + r32) * 136 + (32 * kt + 16 * i + 4 * hi) * 2;
;                         const s16x4 lo = *(const LAS s16x4*)vq, h4 = *(const LAS s16x4*)(vq + 16);
;                         const bf16x8 a = {lo[0], lo[1], lo[2], lo[3], h4[0], h4[1], h4[2], h4[3]};
;                         o[dt] = __builtin_amdgcn_mfma_f32_32x32x16_bf16(a, pb[kt][i], o[dt], 0, 0, 0);
;                     }
;                     ol = __builtin_amdgcn_mfma_f32_32x32x16_bf16(ones, pb[kt][i], ol, 0, 0, 0);
;                 }
.LBB0_750:
	v_exp_f32_e32 v96, v96
	v_exp_f32_e32 v97, v97
	v_exp_f32_e32 v98, v98
	v_exp_f32_e32 v99, v99
	v_exp_f32_e32 v100, v100
	v_exp_f32_e32 v101, v101
	v_exp_f32_e32 v102, v102
	v_exp_f32_e32 v103, v103
	v_cvt_pk_bf16_f32 v6, v96, v97
	v_cvt_pk_bf16_f32 v7, v98, v99
	v_cvt_pk_bf16_f32 v8, v100, v101
	v_cvt_pk_bf16_f32 v9, v102, v103
	v_exp_f32_e32 v104, v104
	v_exp_f32_e32 v105, v105
	s_waitcnt lgkmcnt(6)
	v_mfma_f32_32x32x16_bf16 v[32:47], v[164:167], v[6:9], v[32:47]
	v_exp_f32_e32 v106, v106
	v_exp_f32_e32 v107, v107
	v_cvt_pk_bf16_f32 v208, v104, v105
	v_mfma_f32_32x32x16_bf16 v[16:31], v[168:171], v[6:9], v[16:31]
	v_exp_f32_e32 v108, v108
	v_exp_f32_e32 v109, v109
	v_cvt_pk_bf16_f32 v209, v106, v107
	v_mfma_f32_32x32x16_bf16 v[64:79], v[204:207], v[6:9], v[64:79]
	v_exp_f32_e32 v110, v110
	v_exp_f32_e32 v111, v111
	v_cvt_pk_bf16_f32 v210, v108, v109
	v_exp_f32_e32 v80, v80
	v_cvt_pk_bf16_f32 v211, v110, v111
	v_exp_f32_e32 v81, v81
	s_waitcnt lgkmcnt(4)
	v_mfma_f32_32x32x16_bf16 v[32:47], v[172:175], v[208:211], v[32:47]
	v_exp_f32_e32 v82, v82
	v_exp_f32_e32 v83, v83
	v_cvt_pk_bf16_f32 v6, v80, v81
	v_mfma_f32_32x32x16_bf16 v[16:31], v[180:183], v[208:211], v[16:31]
	v_exp_f32_e32 v84, v84
	v_exp_f32_e32 v85, v85
	v_cvt_pk_bf16_f32 v7, v82, v83
	v_mfma_f32_32x32x16_bf16 v[64:79], v[204:207], v[208:211], v[64:79]
	v_exp_f32_e32 v86, v86
	v_exp_f32_e32 v87, v87
	v_cvt_pk_bf16_f32 v8, v84, v85
	v_exp_f32_e32 v88, v88
	v_cvt_pk_bf16_f32 v9, v86, v87
	v_exp_f32_e32 v89, v89
	s_waitcnt lgkmcnt(2)
	v_mfma_f32_32x32x16_bf16 v[32:47], v[184:187], v[6:9], v[32:47]
	v_exp_f32_e32 v90, v90
	v_exp_f32_e32 v91, v91
	v_cvt_pk_bf16_f32 v208, v88, v89
	v_mfma_f32_32x32x16_bf16 v[16:31], v[188:191], v[6:9], v[16:31]
	v_exp_f32_e32 v92, v92
	v_exp_f32_e32 v93, v93
	v_cvt_pk_bf16_f32 v209, v90, v91
	v_mfma_f32_32x32x16_bf16 v[64:79], v[204:207], v[6:9], v[64:79]
	v_exp_f32_e32 v94, v94
	v_exp_f32_e32 v95, v95
	v_cvt_pk_bf16_f32 v210, v92, v93
	s_nop 0
	v_cvt_pk_bf16_f32 v211, v94, v95
	s_waitcnt lgkmcnt(0)
	s_nop 0
	v_mfma_f32_32x32x16_bf16 v[32:47], v[192:195], v[208:211], v[32:47]
	v_mfma_f32_32x32x16_bf16 v[16:31], v[196:199], v[208:211], v[16:31]
	v_mfma_f32_32x32x16_bf16 v[64:79], v[204:207], v[208:211], v[64:79]
	s_andn2_b64 vcc, exec, s[4:5]
	s_cbranch_vccz .LBB0_744
	s_branch .LBB0_745
